# residual GEMM epilogues (w2 both layers, out-proj layer 1): batched loads then all stores with scalar-base addressing, instead of 8 serialized load/wait/fma/store blocks
# baseline (speedup 1.0000x reference)
; __device__ __forceinline__ int crow(int r, int hi) { return (r & 3) + 8 * (r >> 2) + 4 * hi; }
; __device__ __forceinline__ void phase_gemm_res(const Params& p, int L, const bf16_t* __restrict__ A, int K, const bf16_t* __restrict__ WT, int gate_slot, bool from_input, bool xonly, LP lds) {
;     ...
;   for (int t = blockIdx.x; t < 512; t += gridDim.x) {
;     int row0 = 0, col0 = 0, rown = 0, coln = 0;
;     tile_of(t, row0, col0);
;     const bool hasn = tile_of(t + gridDim.x, rown, coln);
;     const float* gate = mods + (size_t)mod_idx(row0) * 6144;
;     const float* resb = from_input ? in_row(p, row0) : s_row(p, row0);
;     float* sb = s_row(p, row0);
;     gemm8p(A + (size_t)row0 * K, K, WT + (size_t)col0 * K, K, K, lds, [&](int rr, int cc, int hi, f32x16 v) __attribute__((always_inline)) {
;       const int col = col0 + cc; const float g = gate[col];
; #pragma unroll
;       for (int r = 0; r < 16; ++r) { const size_t o = (size_t)(rr + crow(r, hi)) * DM + col; sb[o] = resb[o] + g * v[r]; }
.LBB0_1818:
	s_mul_hi_i32 s59, s58, 0x3e0f83e1
	s_lshr_b32 s60, s59, 31
	s_ashr_i32 s59, s59, 11
	s_add_i32 s64, s59, s60
	s_mul_i32 s59, s64, 0xffffdf00
	s_add_i32 s62, s59, s58
	s_cmpk_lt_i32 s62, 0x100
	s_cselect_b64 s[58:59], -1, 0
	s_and_b64 s[60:61], s[58:59], exec
	s_cselect_b32 s60, 4, s64
	s_mul_hi_i32 s61, s60, 0x6000
	s_mulk_i32 s60, 0x6000
	s_add_u32 s60, s71, s60
	s_addc_u32 s61, s72, s61
	s_ashr_i32 s65, s64, 31
	s_add_i32 s66, s62, 0xffffff00
	s_ashr_i32 s67, s62, 31
	s_and_b64 s[58:59], s[58:59], exec
	s_cselect_b32 s58, s62, s66
	s_cselect_b32 s62, 20, 25
	s_cselect_b32 s81, s76, s3
	s_cselect_b32 s82, s73, s2
	s_cselect_b32 s59, s67, 0
	s_lshl_b64 s[64:65], s[64:65], s62
	s_add_u32 s62, s82, s64
	s_addc_u32 s64, s81, s65
	s_lshl_b64 s[58:59], s[58:59], 12
	s_add_u32 s58, s62, s58
	s_addc_u32 s59, s64, s59
	s_nop 0
	v_lshl_add_u32 v128, v149, 2, v150
	v_add_u32_e32 v230, s63, v151
	v_lshlrev_b32_e32 v230, 2, v230
	v_lshl_add_u32 v128, v128, 12, v230
	v_add_u32_e32 v130, 0x1000, v128
	v_add_u32_e32 v131, 0x2000, v128
	v_add_u32_e32 v229, 0x3000, v128
	global_load_dword v231, v230, s[60:61]
	global_load_dword v232, v230, s[60:61] offset:512
	s_add_u32 s98, s58, 0x0
	s_addc_u32 s99, s59, 0
	global_load_dword v132, v128, s[98:99]
	global_load_dword v133, v130, s[98:99]
	global_load_dword v134, v131, s[98:99]
	global_load_dword v135, v229, s[98:99]
	global_load_dword v136, v128, s[98:99] offset:512
	global_load_dword v137, v130, s[98:99] offset:512
	global_load_dword v138, v131, s[98:99] offset:512
	global_load_dword v139, v229, s[98:99] offset:512
	s_add_u32 s98, s98, 0x8000
	s_addc_u32 s99, s99, 0
	global_load_dword v140, v128, s[98:99]
	global_load_dword v141, v130, s[98:99]
	global_load_dword v142, v131, s[98:99]
	global_load_dword v143, v229, s[98:99]
	global_load_dword v144, v128, s[98:99] offset:512
	global_load_dword v145, v130, s[98:99] offset:512
	global_load_dword v146, v131, s[98:99] offset:512
	global_load_dword v147, v229, s[98:99] offset:512
	s_add_u32 s98, s98, 0x8000
	s_addc_u32 s99, s99, 0
	global_load_dword v148, v128, s[98:99]
	global_load_dword v149, v130, s[98:99]
	global_load_dword v150, v131, s[98:99]
	global_load_dword v151, v229, s[98:99]
	global_load_dword v152, v128, s[98:99] offset:512
	global_load_dword v153, v130, s[98:99] offset:512
	global_load_dword v154, v131, s[98:99] offset:512
	global_load_dword v155, v229, s[98:99] offset:512
	s_add_u32 s98, s98, 0x8000
	s_addc_u32 s99, s99, 0
	global_load_dword v156, v128, s[98:99]
	global_load_dword v157, v130, s[98:99]
	global_load_dword v158, v131, s[98:99]
	global_load_dword v159, v229, s[98:99]
	global_load_dword v160, v128, s[98:99] offset:512
	global_load_dword v161, v130, s[98:99] offset:512
	global_load_dword v162, v131, s[98:99] offset:512
	global_load_dword v163, v229, s[98:99] offset:512
	s_add_u32 s98, s98, 0x8000
	s_addc_u32 s99, s99, 0
	global_load_dword v164, v128, s[98:99]
	global_load_dword v165, v130, s[98:99]
	global_load_dword v166, v131, s[98:99]
	global_load_dword v167, v229, s[98:99]
	global_load_dword v168, v128, s[98:99] offset:512
	global_load_dword v169, v130, s[98:99] offset:512
	global_load_dword v170, v131, s[98:99] offset:512
	global_load_dword v171, v229, s[98:99] offset:512
	s_add_u32 s98, s98, 0x8000
	s_addc_u32 s99, s99, 0
	global_load_dword v172, v128, s[98:99]
	global_load_dword v173, v130, s[98:99]
	global_load_dword v174, v131, s[98:99]
	global_load_dword v175, v229, s[98:99]
	global_load_dword v176, v128, s[98:99] offset:512
	global_load_dword v177, v130, s[98:99] offset:512
	global_load_dword v178, v131, s[98:99] offset:512
	global_load_dword v179, v229, s[98:99] offset:512
	s_add_u32 s98, s98, 0x8000
	s_addc_u32 s99, s99, 0
	global_load_dword v180, v128, s[98:99]
	global_load_dword v181, v130, s[98:99]
	global_load_dword v182, v131, s[98:99]
	global_load_dword v183, v229, s[98:99]
	global_load_dword v184, v128, s[98:99] offset:512
	global_load_dword v185, v130, s[98:99] offset:512
	global_load_dword v186, v131, s[98:99] offset:512
	global_load_dword v187, v229, s[98:99] offset:512
	s_add_u32 s98, s98, 0x8000
	s_addc_u32 s99, s99, 0
	global_load_dword v188, v128, s[98:99]
	global_load_dword v189, v130, s[98:99]
	global_load_dword v191, v131, s[98:99]
	global_load_dword v192, v229, s[98:99]
	global_load_dword v193, v128, s[98:99] offset:512
	global_load_dword v194, v130, s[98:99] offset:512
	global_load_dword v195, v131, s[98:99] offset:512
	global_load_dword v196, v229, s[98:99] offset:512
	s_add_u32 s98, s98, 0x48000
	s_addc_u32 s99, s99, 0
	global_load_dword v197, v128, s[98:99]
	global_load_dword v198, v130, s[98:99]
	global_load_dword v199, v131, s[98:99]
	global_load_dword v200, v229, s[98:99]
	global_load_dword v201, v128, s[98:99] offset:512
	global_load_dword v202, v130, s[98:99] offset:512
	global_load_dword v203, v131, s[98:99] offset:512
	global_load_dword v204, v229, s[98:99] offset:512
	s_add_u32 s98, s98, 0x8000
	s_addc_u32 s99, s99, 0
	global_load_dword v205, v128, s[98:99]
	global_load_dword v206, v130, s[98:99]
	global_load_dword v207, v131, s[98:99]
	global_load_dword v208, v229, s[98:99]
	global_load_dword v209, v128, s[98:99] offset:512
	global_load_dword v210, v130, s[98:99] offset:512
	global_load_dword v211, v131, s[98:99] offset:512
	global_load_dword v212, v229, s[98:99] offset:512
	s_add_u32 s98, s98, 0x8000
	s_addc_u32 s99, s99, 0
	global_load_dword v213, v128, s[98:99]
	global_load_dword v214, v130, s[98:99]
	global_load_dword v215, v131, s[98:99]
	global_load_dword v216, v229, s[98:99]
	global_load_dword v217, v128, s[98:99] offset:512
	global_load_dword v218, v130, s[98:99] offset:512
	global_load_dword v219, v131, s[98:99] offset:512
	global_load_dword v220, v229, s[98:99] offset:512
	s_add_u32 s98, s98, 0x8000
	s_addc_u32 s99, s99, 0
	global_load_dword v221, v128, s[98:99]
	global_load_dword v222, v130, s[98:99]
	global_load_dword v223, v131, s[98:99]
	global_load_dword v224, v229, s[98:99]
	global_load_dword v225, v128, s[98:99] offset:512
	global_load_dword v226, v130, s[98:99] offset:512
	global_load_dword v227, v131, s[98:99] offset:512
	global_load_dword v228, v229, s[98:99] offset:512
	s_waitcnt vmcnt(0)
; __device__ __forceinline__ int crow(int r, int hi) { return (r & 3) + 8 * (r >> 2) + 4 * hi; }
; __device__ __forceinline__ void phase_gemm_res(const Params& p, int L, const bf16_t* __restrict__ A, int K, const bf16_t* __restrict__ WT, int gate_slot, bool from_input, bool xonly, LP lds) {
;     ...
;     gemm8p(A + (size_t)row0 * K, K, WT + (size_t)col0 * K, K, K, lds, [&](int rr, int cc, int hi, f32x16 v) __attribute__((always_inline)) {
;       const int col = col0 + cc; const float g = gate[col];
; #pragma unroll
;       for (int r = 0; r < 16; ++r) { const size_t o = (size_t)(rr + crow(r, hi)) * DM + col; sb[o] = resb[o] + g * v[r]; }
	v_fma_f32 v112, v112, v231, v132
	v_fma_f32 v113, v113, v231, v133
	v_fma_f32 v114, v114, v231, v134
	v_fma_f32 v115, v115, v231, v135
	v_fma_f32 v80, v80, v232, v136
	v_fma_f32 v81, v81, v232, v137
	v_fma_f32 v82, v82, v232, v138
	v_fma_f32 v83, v83, v232, v139
	v_fma_f32 v116, v116, v231, v140
	v_fma_f32 v117, v117, v231, v141
	v_fma_f32 v118, v118, v231, v142
	v_fma_f32 v119, v119, v231, v143
	v_fma_f32 v84, v84, v232, v144
	v_fma_f32 v85, v85, v232, v145
	v_fma_f32 v86, v86, v232, v146
	v_fma_f32 v87, v87, v232, v147
	v_fma_f32 v120, v120, v231, v148
	v_fma_f32 v121, v121, v231, v149
	v_fma_f32 v122, v122, v231, v150
	v_fma_f32 v123, v123, v231, v151
	v_fma_f32 v88, v88, v232, v152
	v_fma_f32 v89, v89, v232, v153
	v_fma_f32 v90, v90, v232, v154
	v_fma_f32 v91, v91, v232, v155
	v_fma_f32 v124, v124, v231, v156
	v_fma_f32 v125, v125, v231, v157
	v_fma_f32 v126, v126, v231, v158
	v_fma_f32 v127, v127, v231, v159
	v_fma_f32 v92, v92, v232, v160
	v_fma_f32 v93, v93, v232, v161
	v_fma_f32 v94, v94, v232, v162
	v_fma_f32 v95, v95, v232, v163
	v_fma_f32 v96, v96, v231, v164
	v_fma_f32 v97, v97, v231, v165
	v_fma_f32 v98, v98, v231, v166
	v_fma_f32 v99, v99, v231, v167
	v_fma_f32 v64, v64, v232, v168
	v_fma_f32 v65, v65, v232, v169
	v_fma_f32 v66, v66, v232, v170
	v_fma_f32 v67, v67, v232, v171
	v_fma_f32 v100, v100, v231, v172
	v_fma_f32 v101, v101, v231, v173
	v_fma_f32 v102, v102, v231, v174
	v_fma_f32 v103, v103, v231, v175
	v_fma_f32 v68, v68, v232, v176
	v_fma_f32 v69, v69, v232, v177
	v_fma_f32 v70, v70, v232, v178
	v_fma_f32 v71, v71, v232, v179
	v_fma_f32 v104, v104, v231, v180
	v_fma_f32 v105, v105, v231, v181
	v_fma_f32 v106, v106, v231, v182
	v_fma_f32 v107, v107, v231, v183
	v_fma_f32 v72, v72, v232, v184
	v_fma_f32 v73, v73, v232, v185
	v_fma_f32 v74, v74, v232, v186
	v_fma_f32 v75, v75, v232, v187
	v_fma_f32 v108, v108, v231, v188
	v_fma_f32 v109, v109, v231, v189
	v_fma_f32 v110, v110, v231, v191
	v_fma_f32 v111, v111, v231, v192
	v_fma_f32 v76, v76, v232, v193
	v_fma_f32 v77, v77, v232, v194
	v_fma_f32 v78, v78, v232, v195
	v_fma_f32 v79, v79, v232, v196
	v_fma_f32 v48, v48, v231, v197
	v_fma_f32 v49, v49, v231, v198
	v_fma_f32 v50, v50, v231, v199
	v_fma_f32 v51, v51, v231, v200
	v_fma_f32 v16, v16, v232, v201
	v_fma_f32 v17, v17, v232, v202
	v_fma_f32 v18, v18, v232, v203
	v_fma_f32 v19, v19, v232, v204
	v_fma_f32 v52, v52, v231, v205
	v_fma_f32 v53, v53, v231, v206
	v_fma_f32 v54, v54, v231, v207
	v_fma_f32 v55, v55, v231, v208
	v_fma_f32 v20, v20, v232, v209
	v_fma_f32 v21, v21, v232, v210
	v_fma_f32 v22, v22, v232, v211
	v_fma_f32 v23, v23, v232, v212
	v_fma_f32 v56, v56, v231, v213
	v_fma_f32 v57, v57, v231, v214
	v_fma_f32 v58, v58, v231, v215
	v_fma_f32 v59, v59, v231, v216
	v_fma_f32 v24, v24, v232, v217
	v_fma_f32 v25, v25, v232, v218
	v_fma_f32 v26, v26, v232, v219
	v_fma_f32 v27, v27, v232, v220
	v_fma_f32 v60, v60, v231, v221
	v_fma_f32 v61, v61, v231, v222
	v_fma_f32 v62, v62, v231, v223
	v_fma_f32 v63, v63, v231, v224
	v_fma_f32 v28, v28, v232, v225
	v_fma_f32 v29, v29, v232, v226
	v_fma_f32 v30, v30, v232, v227
	v_fma_f32 v31, v31, v232, v228
	s_add_u32 s98, s58, 0xa0000
	s_addc_u32 s99, s59, 0
	global_load_dword v132, v128, s[98:99]
	global_load_dword v133, v130, s[98:99]
	global_load_dword v134, v131, s[98:99]
	global_load_dword v135, v229, s[98:99]
	global_load_dword v136, v128, s[98:99] offset:512
	global_load_dword v137, v130, s[98:99] offset:512
	global_load_dword v138, v131, s[98:99] offset:512
	global_load_dword v139, v229, s[98:99] offset:512
	s_add_u32 s98, s98, 0x8000
	s_addc_u32 s99, s99, 0
	global_load_dword v140, v128, s[98:99]
	global_load_dword v141, v130, s[98:99]
	global_load_dword v142, v131, s[98:99]
	global_load_dword v143, v229, s[98:99]
	global_load_dword v144, v128, s[98:99] offset:512
	global_load_dword v145, v130, s[98:99] offset:512
	global_load_dword v146, v131, s[98:99] offset:512
	global_load_dword v147, v229, s[98:99] offset:512
	s_add_u32 s98, s98, 0x8000
	s_addc_u32 s99, s99, 0
	global_load_dword v148, v128, s[98:99]
	global_load_dword v149, v130, s[98:99]
	global_load_dword v150, v131, s[98:99]
	global_load_dword v151, v229, s[98:99]
	global_load_dword v152, v128, s[98:99] offset:512
	global_load_dword v153, v130, s[98:99] offset:512
	global_load_dword v154, v131, s[98:99] offset:512
	global_load_dword v155, v229, s[98:99] offset:512
	s_add_u32 s98, s98, 0x8000
	s_addc_u32 s99, s99, 0
	global_load_dword v156, v128, s[98:99]
	global_load_dword v157, v130, s[98:99]
	global_load_dword v158, v131, s[98:99]
	global_load_dword v159, v229, s[98:99]
	global_load_dword v160, v128, s[98:99] offset:512
	global_load_dword v161, v130, s[98:99] offset:512
	global_load_dword v162, v131, s[98:99] offset:512
	global_load_dword v163, v229, s[98:99] offset:512
	s_waitcnt vmcnt(0)
; __device__ __forceinline__ int crow(int r, int hi) { return (r & 3) + 8 * (r >> 2) + 4 * hi; }
; __device__ __forceinline__ void phase_gemm_res(const Params& p, int L, const bf16_t* __restrict__ A, int K, const bf16_t* __restrict__ WT, int gate_slot, bool from_input, bool xonly, LP lds) {
;     ...
;     gemm8p(A + (size_t)row0 * K, K, WT + (size_t)col0 * K, K, K, lds, [&](int rr, int cc, int hi, f32x16 v) __attribute__((always_inline)) {
;       const int col = col0 + cc; const float g = gate[col];
; #pragma unroll
;       for (int r = 0; r < 16; ++r) { const size_t o = (size_t)(rr + crow(r, hi)) * DM + col; sb[o] = resb[o] + g * v[r]; }
	v_fma_f32 v32, v32, v231, v132
	v_fma_f32 v33, v33, v231, v133
	v_fma_f32 v34, v34, v231, v134
	v_fma_f32 v35, v35, v231, v135
	v_fma_f32 v0, v0, v232, v136
	v_fma_f32 v1, v1, v232, v137
	v_fma_f32 v2, v2, v232, v138
	v_fma_f32 v3, v3, v232, v139
	v_fma_f32 v36, v36, v231, v140
	v_fma_f32 v37, v37, v231, v141
	v_fma_f32 v38, v38, v231, v142
	v_fma_f32 v39, v39, v231, v143
	v_fma_f32 v4, v4, v232, v144
	v_fma_f32 v5, v5, v232, v145
	v_fma_f32 v6, v6, v232, v146
	v_fma_f32 v7, v7, v232, v147
	v_fma_f32 v40, v40, v231, v148
	v_fma_f32 v41, v41, v231, v149
	v_fma_f32 v42, v42, v231, v150
	v_fma_f32 v43, v43, v231, v151
	v_fma_f32 v8, v8, v232, v152
	v_fma_f32 v9, v9, v232, v153
	v_fma_f32 v10, v10, v232, v154
	v_fma_f32 v11, v11, v232, v155
	v_fma_f32 v44, v44, v231, v156
	v_fma_f32 v45, v45, v231, v157
	v_fma_f32 v46, v46, v231, v158
	v_fma_f32 v47, v47, v231, v159
	v_fma_f32 v12, v12, v232, v160
	v_fma_f32 v13, v13, v232, v161
	v_fma_f32 v14, v14, v232, v162
	v_fma_f32 v15, v15, v232, v163
	s_add_u32 s98, s58, 0x0
	s_addc_u32 s99, s59, 0
	global_store_dword v128, v112, s[98:99]
	global_store_dword v130, v113, s[98:99]
	global_store_dword v131, v114, s[98:99]
	global_store_dword v229, v115, s[98:99]
	global_store_dword v128, v80, s[98:99] offset:512
	global_store_dword v130, v81, s[98:99] offset:512
	global_store_dword v131, v82, s[98:99] offset:512
	global_store_dword v229, v83, s[98:99] offset:512
	s_add_u32 s98, s98, 0x8000
	s_addc_u32 s99, s99, 0
	global_store_dword v128, v116, s[98:99]
	global_store_dword v130, v117, s[98:99]
	global_store_dword v131, v118, s[98:99]
	global_store_dword v229, v119, s[98:99]
	global_store_dword v128, v84, s[98:99] offset:512
	global_store_dword v130, v85, s[98:99] offset:512
	global_store_dword v131, v86, s[98:99] offset:512
	global_store_dword v229, v87, s[98:99] offset:512
	s_add_u32 s98, s98, 0x8000
	s_addc_u32 s99, s99, 0
	global_store_dword v128, v120, s[98:99]
	global_store_dword v130, v121, s[98:99]
	global_store_dword v131, v122, s[98:99]
	global_store_dword v229, v123, s[98:99]
	global_store_dword v128, v88, s[98:99] offset:512
	global_store_dword v130, v89, s[98:99] offset:512
	global_store_dword v131, v90, s[98:99] offset:512
	global_store_dword v229, v91, s[98:99] offset:512
	s_add_u32 s98, s98, 0x8000
	s_addc_u32 s99, s99, 0
	global_store_dword v128, v124, s[98:99]
	global_store_dword v130, v125, s[98:99]
	global_store_dword v131, v126, s[98:99]
	global_store_dword v229, v127, s[98:99]
	global_store_dword v128, v92, s[98:99] offset:512
	global_store_dword v130, v93, s[98:99] offset:512
	global_store_dword v131, v94, s[98:99] offset:512
	global_store_dword v229, v95, s[98:99] offset:512
	s_add_u32 s98, s98, 0x8000
	s_addc_u32 s99, s99, 0
	global_store_dword v128, v96, s[98:99]
	global_store_dword v130, v97, s[98:99]
	global_store_dword v131, v98, s[98:99]
	global_store_dword v229, v99, s[98:99]
	global_store_dword v128, v64, s[98:99] offset:512
	global_store_dword v130, v65, s[98:99] offset:512
	global_store_dword v131, v66, s[98:99] offset:512
	global_store_dword v229, v67, s[98:99] offset:512
	s_add_u32 s98, s98, 0x8000
	s_addc_u32 s99, s99, 0
	global_store_dword v128, v100, s[98:99]
	global_store_dword v130, v101, s[98:99]
	global_store_dword v131, v102, s[98:99]
	global_store_dword v229, v103, s[98:99]
	global_store_dword v128, v68, s[98:99] offset:512
	global_store_dword v130, v69, s[98:99] offset:512
	global_store_dword v131, v70, s[98:99] offset:512
	global_store_dword v229, v71, s[98:99] offset:512
	s_add_u32 s98, s98, 0x8000
	s_addc_u32 s99, s99, 0
	global_store_dword v128, v104, s[98:99]
	global_store_dword v130, v105, s[98:99]
	global_store_dword v131, v106, s[98:99]
	global_store_dword v229, v107, s[98:99]
	global_store_dword v128, v72, s[98:99] offset:512
	global_store_dword v130, v73, s[98:99] offset:512
	global_store_dword v131, v74, s[98:99] offset:512
	global_store_dword v229, v75, s[98:99] offset:512
; __device__ __forceinline__ int crow(int r, int hi) { return (r & 3) + 8 * (r >> 2) + 4 * hi; }
; __device__ __forceinline__ void phase_gemm_res(const Params& p, int L, const bf16_t* __restrict__ A, int K, const bf16_t* __restrict__ WT, int gate_slot, bool from_input, bool xonly, LP lds) {
;     ...
;     gemm8p(A + (size_t)row0 * K, K, WT + (size_t)col0 * K, K, K, lds, [&](int rr, int cc, int hi, f32x16 v) __attribute__((always_inline)) {
;       const int col = col0 + cc; const float g = gate[col];
; #pragma unroll
;       for (int r = 0; r < 16; ++r) { const size_t o = (size_t)(rr + crow(r, hi)) * DM + col; sb[o] = resb[o] + g * v[r]; }
;     }, pre, hasn ? A + (size_t)rown * K : nullptr, hasn ? WT + (size_t)coln * K : nullptr);
;     pre = hasn;
;   }
	s_add_u32 s98, s98, 0x8000
	s_addc_u32 s99, s99, 0
	global_store_dword v128, v108, s[98:99]
	global_store_dword v130, v109, s[98:99]
	global_store_dword v131, v110, s[98:99]
	global_store_dword v229, v111, s[98:99]
	global_store_dword v128, v76, s[98:99] offset:512
	global_store_dword v130, v77, s[98:99] offset:512
	global_store_dword v131, v78, s[98:99] offset:512
	global_store_dword v229, v79, s[98:99] offset:512
	s_add_u32 s98, s98, 0x48000
	s_addc_u32 s99, s99, 0
	global_store_dword v128, v48, s[98:99]
	global_store_dword v130, v49, s[98:99]
	global_store_dword v131, v50, s[98:99]
	global_store_dword v229, v51, s[98:99]
	global_store_dword v128, v16, s[98:99] offset:512
	global_store_dword v130, v17, s[98:99] offset:512
	global_store_dword v131, v18, s[98:99] offset:512
	global_store_dword v229, v19, s[98:99] offset:512
	s_add_u32 s98, s98, 0x8000
	s_addc_u32 s99, s99, 0
	global_store_dword v128, v52, s[98:99]
	global_store_dword v130, v53, s[98:99]
	global_store_dword v131, v54, s[98:99]
	global_store_dword v229, v55, s[98:99]
	global_store_dword v128, v20, s[98:99] offset:512
	global_store_dword v130, v21, s[98:99] offset:512
	global_store_dword v131, v22, s[98:99] offset:512
	global_store_dword v229, v23, s[98:99] offset:512
	s_add_u32 s98, s98, 0x8000
	s_addc_u32 s99, s99, 0
	global_store_dword v128, v56, s[98:99]
	global_store_dword v130, v57, s[98:99]
	global_store_dword v131, v58, s[98:99]
	global_store_dword v229, v59, s[98:99]
	global_store_dword v128, v24, s[98:99] offset:512
	global_store_dword v130, v25, s[98:99] offset:512
	global_store_dword v131, v26, s[98:99] offset:512
	global_store_dword v229, v27, s[98:99] offset:512
	s_add_u32 s98, s98, 0x8000
	s_addc_u32 s99, s99, 0
	global_store_dword v128, v60, s[98:99]
	global_store_dword v130, v61, s[98:99]
	global_store_dword v131, v62, s[98:99]
	global_store_dword v229, v63, s[98:99]
	global_store_dword v128, v28, s[98:99] offset:512
	global_store_dword v130, v29, s[98:99] offset:512
	global_store_dword v131, v30, s[98:99] offset:512
	global_store_dword v229, v31, s[98:99] offset:512
	s_add_u32 s98, s98, 0x8000
	s_addc_u32 s99, s99, 0
	global_store_dword v128, v32, s[98:99]
	global_store_dword v130, v33, s[98:99]
	global_store_dword v131, v34, s[98:99]
	global_store_dword v229, v35, s[98:99]
	global_store_dword v128, v0, s[98:99] offset:512
	global_store_dword v130, v1, s[98:99] offset:512
	global_store_dword v131, v2, s[98:99] offset:512
	global_store_dword v229, v3, s[98:99] offset:512
	s_add_u32 s98, s98, 0x8000
	s_addc_u32 s99, s99, 0
	global_store_dword v128, v36, s[98:99]
	global_store_dword v130, v37, s[98:99]
	global_store_dword v131, v38, s[98:99]
	global_store_dword v229, v39, s[98:99]
	global_store_dword v128, v4, s[98:99] offset:512
	global_store_dword v130, v5, s[98:99] offset:512
	global_store_dword v131, v6, s[98:99] offset:512
	global_store_dword v229, v7, s[98:99] offset:512
	s_add_u32 s98, s98, 0x8000
	s_addc_u32 s99, s99, 0
	global_store_dword v128, v40, s[98:99]
	global_store_dword v130, v41, s[98:99]
	global_store_dword v131, v42, s[98:99]
	global_store_dword v229, v43, s[98:99]
	global_store_dword v128, v8, s[98:99] offset:512
	global_store_dword v130, v9, s[98:99] offset:512
	global_store_dword v131, v10, s[98:99] offset:512
	global_store_dword v229, v11, s[98:99] offset:512
	s_add_u32 s98, s98, 0x8000
	s_addc_u32 s99, s99, 0
	global_store_dword v128, v44, s[98:99]
	global_store_dword v130, v45, s[98:99]
	global_store_dword v131, v46, s[98:99]
	global_store_dword v229, v47, s[98:99]
	global_store_dword v128, v12, s[98:99] offset:512
	global_store_dword v130, v13, s[98:99] offset:512
	global_store_dword v131, v14, s[98:99] offset:512
	global_store_dword v229, v15, s[98:99] offset:512
	s_add_i32 s77, s77, s78
	s_add_i32 s79, s79, s34
	s_mov_b64 s[58:59], -1
	s_and_b64 vcc, exec, s[56:57]
	s_mov_b32 s82, s80
	s_cbranch_vccnz .LBB0_1831

; __device__ __forceinline__ int crow(int r, int hi) { return (r & 3) + 8 * (r >> 2) + 4 * hi; }
; __device__ __forceinline__ void phase_gemm_res(const Params& p, int L, const bf16_t* __restrict__ A, int K, const bf16_t* __restrict__ WT, int gate_slot, bool from_input, bool xonly, LP lds) {
;     ...
;     const float* gate = mods + (size_t)mod_idx(row0) * 6144;
;     const float* resb = from_input ? in_row(p, row0) : s_row(p, row0);
;     float* sb = s_row(p, row0);
;     gemm8p(A + (size_t)row0 * K, K, WT + (size_t)col0 * K, K, K, lds, [&](int rr, int cc, int hi, f32x16 v) __attribute__((always_inline)) {
;       const int col = col0 + cc; const float g = gate[col];
; #pragma unroll
;       for (int r = 0; r < 16; ++r) { const size_t o = (size_t)(rr + crow(r, hi)) * DM + col; sb[o] = resb[o] + g * v[r]; }
.LBB0_2195:
	s_mul_hi_i32 s63, s62, 0x3e0f83e1
	s_lshr_b32 s64, s63, 31
	s_ashr_i32 s63, s63, 11
	s_add_i32 s68, s63, s64
	s_mul_i32 s63, s68, 0xffffdf00
	s_add_i32 s66, s63, s62
	s_cmpk_lt_i32 s66, 0x100
	s_cselect_b64 s[62:63], -1, 0
	s_and_b64 s[64:65], s[62:63], exec
	s_cselect_b32 s64, 4, s68
	s_mul_hi_i32 s65, s64, 0x6000
	s_mulk_i32 s64, 0x6000
	s_add_u32 s64, s76, s64
	s_addc_u32 s65, s77, s65
	s_ashr_i32 s69, s68, 31
	s_add_i32 s70, s66, 0xffffff00
	s_ashr_i32 s71, s66, 31
	s_and_b64 s[62:63], s[62:63], exec
	s_cselect_b32 s62, s66, s70
	s_cselect_b32 s66, 20, 25
	s_cselect_b32 s84, s79, s1
	s_cselect_b32 s85, s78, s0
	s_cselect_b32 s63, s71, 0
	s_lshl_b64 s[68:69], s[68:69], s66
	s_add_u32 s66, s85, s68
	s_addc_u32 s68, s84, s69
	s_lshl_b64 s[62:63], s[62:63], 12
	s_add_u32 s62, s66, s62
	s_addc_u32 s63, s68, s63
	s_nop 0
	v_lshl_add_u32 v128, v149, 2, v150
	v_add_u32_e32 v230, s67, v151
	v_lshlrev_b32_e32 v230, 2, v230
	v_lshl_add_u32 v128, v128, 12, v230
	v_add_u32_e32 v130, 0x1000, v128
	v_add_u32_e32 v131, 0x2000, v128
	v_add_u32_e32 v229, 0x3000, v128
	global_load_dword v231, v230, s[64:65]
	global_load_dword v232, v230, s[64:65] offset:512
	s_add_u32 s98, s62, 0x0
	s_addc_u32 s99, s63, 0
	global_load_dword v132, v128, s[98:99]
	global_load_dword v133, v130, s[98:99]
	global_load_dword v134, v131, s[98:99]
	global_load_dword v135, v229, s[98:99]
	global_load_dword v136, v128, s[98:99] offset:512
	global_load_dword v137, v130, s[98:99] offset:512
	global_load_dword v138, v131, s[98:99] offset:512
	global_load_dword v139, v229, s[98:99] offset:512
	s_add_u32 s98, s98, 0x8000
	s_addc_u32 s99, s99, 0
	global_load_dword v140, v128, s[98:99]
	global_load_dword v141, v130, s[98:99]
	global_load_dword v142, v131, s[98:99]
	global_load_dword v143, v229, s[98:99]
	global_load_dword v144, v128, s[98:99] offset:512
	global_load_dword v145, v130, s[98:99] offset:512
	global_load_dword v146, v131, s[98:99] offset:512
	global_load_dword v147, v229, s[98:99] offset:512
	s_add_u32 s98, s98, 0x8000
	s_addc_u32 s99, s99, 0
	global_load_dword v148, v128, s[98:99]
	global_load_dword v149, v130, s[98:99]
	global_load_dword v150, v131, s[98:99]
	global_load_dword v151, v229, s[98:99]
	global_load_dword v152, v128, s[98:99] offset:512
	global_load_dword v153, v130, s[98:99] offset:512
	global_load_dword v154, v131, s[98:99] offset:512
	global_load_dword v155, v229, s[98:99] offset:512
	s_add_u32 s98, s98, 0x8000
	s_addc_u32 s99, s99, 0
	global_load_dword v156, v128, s[98:99]
	global_load_dword v157, v130, s[98:99]
	global_load_dword v158, v131, s[98:99]
	global_load_dword v159, v229, s[98:99]
	global_load_dword v160, v128, s[98:99] offset:512
	global_load_dword v161, v130, s[98:99] offset:512
	global_load_dword v162, v131, s[98:99] offset:512
	global_load_dword v163, v229, s[98:99] offset:512
	s_add_u32 s98, s98, 0x8000
	s_addc_u32 s99, s99, 0
	global_load_dword v164, v128, s[98:99]
	global_load_dword v165, v130, s[98:99]
	global_load_dword v166, v131, s[98:99]
	global_load_dword v167, v229, s[98:99]
	global_load_dword v168, v128, s[98:99] offset:512
	global_load_dword v169, v130, s[98:99] offset:512
	global_load_dword v170, v131, s[98:99] offset:512
	global_load_dword v171, v229, s[98:99] offset:512
	s_add_u32 s98, s98, 0x8000
	s_addc_u32 s99, s99, 0
	global_load_dword v172, v128, s[98:99]
	global_load_dword v173, v130, s[98:99]
	global_load_dword v174, v131, s[98:99]
	global_load_dword v175, v229, s[98:99]
	global_load_dword v176, v128, s[98:99] offset:512
	global_load_dword v177, v130, s[98:99] offset:512
	global_load_dword v178, v131, s[98:99] offset:512
	global_load_dword v179, v229, s[98:99] offset:512
	s_add_u32 s98, s98, 0x8000
	s_addc_u32 s99, s99, 0
	global_load_dword v180, v128, s[98:99]
	global_load_dword v181, v130, s[98:99]
	global_load_dword v182, v131, s[98:99]
	global_load_dword v183, v229, s[98:99]
	global_load_dword v184, v128, s[98:99] offset:512
	global_load_dword v185, v130, s[98:99] offset:512
	global_load_dword v186, v131, s[98:99] offset:512
	global_load_dword v187, v229, s[98:99] offset:512
	s_add_u32 s98, s98, 0x8000
	s_addc_u32 s99, s99, 0
	global_load_dword v188, v128, s[98:99]
	global_load_dword v189, v130, s[98:99]
	global_load_dword v191, v131, s[98:99]
	global_load_dword v192, v229, s[98:99]
	global_load_dword v193, v128, s[98:99] offset:512
	global_load_dword v194, v130, s[98:99] offset:512
	global_load_dword v195, v131, s[98:99] offset:512
	global_load_dword v196, v229, s[98:99] offset:512
	s_add_u32 s98, s98, 0x48000
	s_addc_u32 s99, s99, 0
	global_load_dword v197, v128, s[98:99]
	global_load_dword v198, v130, s[98:99]
	global_load_dword v199, v131, s[98:99]
	global_load_dword v200, v229, s[98:99]
	global_load_dword v201, v128, s[98:99] offset:512
	global_load_dword v202, v130, s[98:99] offset:512
	global_load_dword v203, v131, s[98:99] offset:512
	global_load_dword v204, v229, s[98:99] offset:512
	s_add_u32 s98, s98, 0x8000
	s_addc_u32 s99, s99, 0
	global_load_dword v205, v128, s[98:99]
	global_load_dword v206, v130, s[98:99]
	global_load_dword v207, v131, s[98:99]
	global_load_dword v208, v229, s[98:99]
	global_load_dword v209, v128, s[98:99] offset:512
	global_load_dword v210, v130, s[98:99] offset:512
	global_load_dword v211, v131, s[98:99] offset:512
	global_load_dword v212, v229, s[98:99] offset:512
	s_add_u32 s98, s98, 0x8000
	s_addc_u32 s99, s99, 0
	global_load_dword v213, v128, s[98:99]
	global_load_dword v214, v130, s[98:99]
	global_load_dword v215, v131, s[98:99]
	global_load_dword v216, v229, s[98:99]
	global_load_dword v217, v128, s[98:99] offset:512
	global_load_dword v218, v130, s[98:99] offset:512
	global_load_dword v219, v131, s[98:99] offset:512
	global_load_dword v220, v229, s[98:99] offset:512
	s_add_u32 s98, s98, 0x8000
	s_addc_u32 s99, s99, 0
	global_load_dword v221, v128, s[98:99]
	global_load_dword v222, v130, s[98:99]
	global_load_dword v223, v131, s[98:99]
	global_load_dword v224, v229, s[98:99]
	global_load_dword v225, v128, s[98:99] offset:512
	global_load_dword v226, v130, s[98:99] offset:512
	global_load_dword v227, v131, s[98:99] offset:512
	global_load_dword v228, v229, s[98:99] offset:512
	s_waitcnt vmcnt(0)
; __device__ __forceinline__ int crow(int r, int hi) { return (r & 3) + 8 * (r >> 2) + 4 * hi; }
; __device__ __forceinline__ void phase_gemm_res(const Params& p, int L, const bf16_t* __restrict__ A, int K, const bf16_t* __restrict__ WT, int gate_slot, bool from_input, bool xonly, LP lds) {
;     ...
;       const int col = col0 + cc; const float g = gate[col];
; #pragma unroll
;       for (int r = 0; r < 16; ++r) { const size_t o = (size_t)(rr + crow(r, hi)) * DM + col; sb[o] = resb[o] + g * v[r]; }
	v_fma_f32 v112, v112, v231, v132
	v_fma_f32 v113, v113, v231, v133
	v_fma_f32 v114, v114, v231, v134
	v_fma_f32 v115, v115, v231, v135
	v_fma_f32 v80, v80, v232, v136
	v_fma_f32 v81, v81, v232, v137
	v_fma_f32 v82, v82, v232, v138
	v_fma_f32 v83, v83, v232, v139
	v_fma_f32 v116, v116, v231, v140
	v_fma_f32 v117, v117, v231, v141
	v_fma_f32 v118, v118, v231, v142
	v_fma_f32 v119, v119, v231, v143
	v_fma_f32 v84, v84, v232, v144
	v_fma_f32 v85, v85, v232, v145
	v_fma_f32 v86, v86, v232, v146
	v_fma_f32 v87, v87, v232, v147
	v_fma_f32 v120, v120, v231, v148
	v_fma_f32 v121, v121, v231, v149
	v_fma_f32 v122, v122, v231, v150
	v_fma_f32 v123, v123, v231, v151
	v_fma_f32 v88, v88, v232, v152
	v_fma_f32 v89, v89, v232, v153
	v_fma_f32 v90, v90, v232, v154
	v_fma_f32 v91, v91, v232, v155
	v_fma_f32 v124, v124, v231, v156
	v_fma_f32 v125, v125, v231, v157
	v_fma_f32 v126, v126, v231, v158
	v_fma_f32 v127, v127, v231, v159
	v_fma_f32 v92, v92, v232, v160
	v_fma_f32 v93, v93, v232, v161
	v_fma_f32 v94, v94, v232, v162
	v_fma_f32 v95, v95, v232, v163
	v_fma_f32 v96, v96, v231, v164
	v_fma_f32 v97, v97, v231, v165
	v_fma_f32 v98, v98, v231, v166
	v_fma_f32 v99, v99, v231, v167
	v_fma_f32 v64, v64, v232, v168
	v_fma_f32 v65, v65, v232, v169
	v_fma_f32 v66, v66, v232, v170
	v_fma_f32 v67, v67, v232, v171
	v_fma_f32 v100, v100, v231, v172
	v_fma_f32 v101, v101, v231, v173
	v_fma_f32 v102, v102, v231, v174
	v_fma_f32 v103, v103, v231, v175
	v_fma_f32 v68, v68, v232, v176
	v_fma_f32 v69, v69, v232, v177
	v_fma_f32 v70, v70, v232, v178
	v_fma_f32 v71, v71, v232, v179
	v_fma_f32 v104, v104, v231, v180
	v_fma_f32 v105, v105, v231, v181
	v_fma_f32 v106, v106, v231, v182
	v_fma_f32 v107, v107, v231, v183
	v_fma_f32 v72, v72, v232, v184
	v_fma_f32 v73, v73, v232, v185
	v_fma_f32 v74, v74, v232, v186
	v_fma_f32 v75, v75, v232, v187
	v_fma_f32 v108, v108, v231, v188
	v_fma_f32 v109, v109, v231, v189
	v_fma_f32 v110, v110, v231, v191
	v_fma_f32 v111, v111, v231, v192
	v_fma_f32 v76, v76, v232, v193
	v_fma_f32 v77, v77, v232, v194
	v_fma_f32 v78, v78, v232, v195
	v_fma_f32 v79, v79, v232, v196
	v_fma_f32 v48, v48, v231, v197
	v_fma_f32 v49, v49, v231, v198
	v_fma_f32 v50, v50, v231, v199
	v_fma_f32 v51, v51, v231, v200
	v_fma_f32 v16, v16, v232, v201
	v_fma_f32 v17, v17, v232, v202
	v_fma_f32 v18, v18, v232, v203
	v_fma_f32 v19, v19, v232, v204
	v_fma_f32 v52, v52, v231, v205
	v_fma_f32 v53, v53, v231, v206
	v_fma_f32 v54, v54, v231, v207
	v_fma_f32 v55, v55, v231, v208
	v_fma_f32 v20, v20, v232, v209
	v_fma_f32 v21, v21, v232, v210
	v_fma_f32 v22, v22, v232, v211
	v_fma_f32 v23, v23, v232, v212
	v_fma_f32 v56, v56, v231, v213
	v_fma_f32 v57, v57, v231, v214
	v_fma_f32 v58, v58, v231, v215
	v_fma_f32 v59, v59, v231, v216
	v_fma_f32 v24, v24, v232, v217
	v_fma_f32 v25, v25, v232, v218
	v_fma_f32 v26, v26, v232, v219
	v_fma_f32 v27, v27, v232, v220
	v_fma_f32 v60, v60, v231, v221
	v_fma_f32 v61, v61, v231, v222
	v_fma_f32 v62, v62, v231, v223
	v_fma_f32 v63, v63, v231, v224
	v_fma_f32 v28, v28, v232, v225
	v_fma_f32 v29, v29, v232, v226
	v_fma_f32 v30, v30, v232, v227
	v_fma_f32 v31, v31, v232, v228
	s_add_u32 s98, s62, 0xa0000
	s_addc_u32 s99, s63, 0
	global_load_dword v132, v128, s[98:99]
	global_load_dword v133, v130, s[98:99]
	global_load_dword v134, v131, s[98:99]
	global_load_dword v135, v229, s[98:99]
	global_load_dword v136, v128, s[98:99] offset:512
	global_load_dword v137, v130, s[98:99] offset:512
	global_load_dword v138, v131, s[98:99] offset:512
	global_load_dword v139, v229, s[98:99] offset:512
	s_add_u32 s98, s98, 0x8000
	s_addc_u32 s99, s99, 0
	global_load_dword v140, v128, s[98:99]
	global_load_dword v141, v130, s[98:99]
	global_load_dword v142, v131, s[98:99]
	global_load_dword v143, v229, s[98:99]
	global_load_dword v144, v128, s[98:99] offset:512
	global_load_dword v145, v130, s[98:99] offset:512
	global_load_dword v146, v131, s[98:99] offset:512
	global_load_dword v147, v229, s[98:99] offset:512
	s_add_u32 s98, s98, 0x8000
	s_addc_u32 s99, s99, 0
	global_load_dword v148, v128, s[98:99]
	global_load_dword v149, v130, s[98:99]
	global_load_dword v150, v131, s[98:99]
	global_load_dword v151, v229, s[98:99]
	global_load_dword v152, v128, s[98:99] offset:512
	global_load_dword v153, v130, s[98:99] offset:512
	global_load_dword v154, v131, s[98:99] offset:512
	global_load_dword v155, v229, s[98:99] offset:512
	s_add_u32 s98, s98, 0x8000
	s_addc_u32 s99, s99, 0
	global_load_dword v156, v128, s[98:99]
	global_load_dword v157, v130, s[98:99]
	global_load_dword v158, v131, s[98:99]
	global_load_dword v159, v229, s[98:99]
	global_load_dword v160, v128, s[98:99] offset:512
	global_load_dword v161, v130, s[98:99] offset:512
	global_load_dword v162, v131, s[98:99] offset:512
	global_load_dword v163, v229, s[98:99] offset:512
	s_waitcnt vmcnt(0)
; __device__ __forceinline__ int crow(int r, int hi) { return (r & 3) + 8 * (r >> 2) + 4 * hi; }
; __device__ __forceinline__ void phase_gemm_res(const Params& p, int L, const bf16_t* __restrict__ A, int K, const bf16_t* __restrict__ WT, int gate_slot, bool from_input, bool xonly, LP lds) {
;     ...
;       const int col = col0 + cc; const float g = gate[col];
; #pragma unroll
;       for (int r = 0; r < 16; ++r) { const size_t o = (size_t)(rr + crow(r, hi)) * DM + col; sb[o] = resb[o] + g * v[r]; }
	v_fma_f32 v32, v32, v231, v132
	v_fma_f32 v33, v33, v231, v133
	v_fma_f32 v34, v34, v231, v134
	v_fma_f32 v35, v35, v231, v135
	v_fma_f32 v0, v0, v232, v136
	v_fma_f32 v1, v1, v232, v137
	v_fma_f32 v2, v2, v232, v138
	v_fma_f32 v3, v3, v232, v139
	v_fma_f32 v36, v36, v231, v140
	v_fma_f32 v37, v37, v231, v141
	v_fma_f32 v38, v38, v231, v142
	v_fma_f32 v39, v39, v231, v143
	v_fma_f32 v4, v4, v232, v144
	v_fma_f32 v5, v5, v232, v145
	v_fma_f32 v6, v6, v232, v146
	v_fma_f32 v7, v7, v232, v147
	v_fma_f32 v40, v40, v231, v148
	v_fma_f32 v41, v41, v231, v149
	v_fma_f32 v42, v42, v231, v150
	v_fma_f32 v43, v43, v231, v151
	v_fma_f32 v8, v8, v232, v152
	v_fma_f32 v9, v9, v232, v153
	v_fma_f32 v10, v10, v232, v154
	v_fma_f32 v11, v11, v232, v155
	v_fma_f32 v44, v44, v231, v156
	v_fma_f32 v45, v45, v231, v157
	v_fma_f32 v46, v46, v231, v158
	v_fma_f32 v47, v47, v231, v159
	v_fma_f32 v12, v12, v232, v160
	v_fma_f32 v13, v13, v232, v161
	v_fma_f32 v14, v14, v232, v162
	v_fma_f32 v15, v15, v232, v163
	s_add_u32 s98, s62, 0x0
	s_addc_u32 s99, s63, 0
	global_store_dword v128, v112, s[98:99]
	global_store_dword v130, v113, s[98:99]
	global_store_dword v131, v114, s[98:99]
	global_store_dword v229, v115, s[98:99]
	global_store_dword v128, v80, s[98:99] offset:512
	global_store_dword v130, v81, s[98:99] offset:512
	global_store_dword v131, v82, s[98:99] offset:512
	global_store_dword v229, v83, s[98:99] offset:512
	s_add_u32 s98, s98, 0x8000
	s_addc_u32 s99, s99, 0
	global_store_dword v128, v116, s[98:99]
	global_store_dword v130, v117, s[98:99]
	global_store_dword v131, v118, s[98:99]
	global_store_dword v229, v119, s[98:99]
	global_store_dword v128, v84, s[98:99] offset:512
	global_store_dword v130, v85, s[98:99] offset:512
	global_store_dword v131, v86, s[98:99] offset:512
	global_store_dword v229, v87, s[98:99] offset:512
	s_add_u32 s98, s98, 0x8000
	s_addc_u32 s99, s99, 0
	global_store_dword v128, v120, s[98:99]
	global_store_dword v130, v121, s[98:99]
	global_store_dword v131, v122, s[98:99]
	global_store_dword v229, v123, s[98:99]
	global_store_dword v128, v88, s[98:99] offset:512
	global_store_dword v130, v89, s[98:99] offset:512
	global_store_dword v131, v90, s[98:99] offset:512
	global_store_dword v229, v91, s[98:99] offset:512
	s_add_u32 s98, s98, 0x8000
	s_addc_u32 s99, s99, 0
	global_store_dword v128, v124, s[98:99]
	global_store_dword v130, v125, s[98:99]
	global_store_dword v131, v126, s[98:99]
	global_store_dword v229, v127, s[98:99]
	global_store_dword v128, v92, s[98:99] offset:512
	global_store_dword v130, v93, s[98:99] offset:512
	global_store_dword v131, v94, s[98:99] offset:512
	global_store_dword v229, v95, s[98:99] offset:512
	s_add_u32 s98, s98, 0x8000
	s_addc_u32 s99, s99, 0
	global_store_dword v128, v96, s[98:99]
	global_store_dword v130, v97, s[98:99]
	global_store_dword v131, v98, s[98:99]
	global_store_dword v229, v99, s[98:99]
	global_store_dword v128, v64, s[98:99] offset:512
	global_store_dword v130, v65, s[98:99] offset:512
	global_store_dword v131, v66, s[98:99] offset:512
	global_store_dword v229, v67, s[98:99] offset:512
	s_add_u32 s98, s98, 0x8000
	s_addc_u32 s99, s99, 0
	global_store_dword v128, v100, s[98:99]
	global_store_dword v130, v101, s[98:99]
	global_store_dword v131, v102, s[98:99]
	global_store_dword v229, v103, s[98:99]
	global_store_dword v128, v68, s[98:99] offset:512
	global_store_dword v130, v69, s[98:99] offset:512
	global_store_dword v131, v70, s[98:99] offset:512
	global_store_dword v229, v71, s[98:99] offset:512
	s_add_u32 s98, s98, 0x8000
	s_addc_u32 s99, s99, 0
	global_store_dword v128, v104, s[98:99]
	global_store_dword v130, v105, s[98:99]
	global_store_dword v131, v106, s[98:99]
	global_store_dword v229, v107, s[98:99]
	global_store_dword v128, v72, s[98:99] offset:512
	global_store_dword v130, v73, s[98:99] offset:512
	global_store_dword v131, v74, s[98:99] offset:512
	global_store_dword v229, v75, s[98:99] offset:512
; __device__ __forceinline__ int crow(int r, int hi) { return (r & 3) + 8 * (r >> 2) + 4 * hi; }
; __device__ __forceinline__ void phase_gemm_res(const Params& p, int L, const bf16_t* __restrict__ A, int K, const bf16_t* __restrict__ WT, int gate_slot, bool from_input, bool xonly, LP lds) {
;     ...
;   for (int t = blockIdx.x; t < 512; t += gridDim.x) {
;     ...
;       const int col = col0 + cc; const float g = gate[col];
; #pragma unroll
;       for (int r = 0; r < 16; ++r) { const size_t o = (size_t)(rr + crow(r, hi)) * DM + col; sb[o] = resb[o] + g * v[r]; }
;     }, pre, hasn ? A + (size_t)rown * K : nullptr, hasn ? WT + (size_t)coln * K : nullptr);
	s_add_u32 s98, s98, 0x8000
	s_addc_u32 s99, s99, 0
	global_store_dword v128, v108, s[98:99]
	global_store_dword v130, v109, s[98:99]
	global_store_dword v131, v110, s[98:99]
	global_store_dword v229, v111, s[98:99]
	global_store_dword v128, v76, s[98:99] offset:512
	global_store_dword v130, v77, s[98:99] offset:512
	global_store_dword v131, v78, s[98:99] offset:512
	global_store_dword v229, v79, s[98:99] offset:512
	s_add_u32 s98, s98, 0x48000
	s_addc_u32 s99, s99, 0
	global_store_dword v128, v48, s[98:99]
	global_store_dword v130, v49, s[98:99]
	global_store_dword v131, v50, s[98:99]
	global_store_dword v229, v51, s[98:99]
	global_store_dword v128, v16, s[98:99] offset:512
	global_store_dword v130, v17, s[98:99] offset:512
	global_store_dword v131, v18, s[98:99] offset:512
	global_store_dword v229, v19, s[98:99] offset:512
	s_add_u32 s98, s98, 0x8000
	s_addc_u32 s99, s99, 0
	global_store_dword v128, v52, s[98:99]
	global_store_dword v130, v53, s[98:99]
	global_store_dword v131, v54, s[98:99]
	global_store_dword v229, v55, s[98:99]
	global_store_dword v128, v20, s[98:99] offset:512
	global_store_dword v130, v21, s[98:99] offset:512
	global_store_dword v131, v22, s[98:99] offset:512
	global_store_dword v229, v23, s[98:99] offset:512
	s_add_u32 s98, s98, 0x8000
	s_addc_u32 s99, s99, 0
	global_store_dword v128, v56, s[98:99]
	global_store_dword v130, v57, s[98:99]
	global_store_dword v131, v58, s[98:99]
	global_store_dword v229, v59, s[98:99]
	global_store_dword v128, v24, s[98:99] offset:512
	global_store_dword v130, v25, s[98:99] offset:512
	global_store_dword v131, v26, s[98:99] offset:512
	global_store_dword v229, v27, s[98:99] offset:512
	s_add_u32 s98, s98, 0x8000
	s_addc_u32 s99, s99, 0
	global_store_dword v128, v60, s[98:99]
	global_store_dword v130, v61, s[98:99]
	global_store_dword v131, v62, s[98:99]
	global_store_dword v229, v63, s[98:99]
	global_store_dword v128, v28, s[98:99] offset:512
	global_store_dword v130, v29, s[98:99] offset:512
	global_store_dword v131, v30, s[98:99] offset:512
	global_store_dword v229, v31, s[98:99] offset:512
	s_add_u32 s98, s98, 0x8000
	s_addc_u32 s99, s99, 0
	global_store_dword v128, v32, s[98:99]
	global_store_dword v130, v33, s[98:99]
	global_store_dword v131, v34, s[98:99]
	global_store_dword v229, v35, s[98:99]
	global_store_dword v128, v0, s[98:99] offset:512
	global_store_dword v130, v1, s[98:99] offset:512
	global_store_dword v131, v2, s[98:99] offset:512
	global_store_dword v229, v3, s[98:99] offset:512
	s_add_u32 s98, s98, 0x8000
	s_addc_u32 s99, s99, 0
	global_store_dword v128, v36, s[98:99]
	global_store_dword v130, v37, s[98:99]
	global_store_dword v131, v38, s[98:99]
	global_store_dword v229, v39, s[98:99]
	global_store_dword v128, v4, s[98:99] offset:512
	global_store_dword v130, v5, s[98:99] offset:512
	global_store_dword v131, v6, s[98:99] offset:512
	global_store_dword v229, v7, s[98:99] offset:512
	s_add_u32 s98, s98, 0x8000
	s_addc_u32 s99, s99, 0
	global_store_dword v128, v40, s[98:99]
	global_store_dword v130, v41, s[98:99]
	global_store_dword v131, v42, s[98:99]
	global_store_dword v229, v43, s[98:99]
	global_store_dword v128, v8, s[98:99] offset:512
	global_store_dword v130, v9, s[98:99] offset:512
	global_store_dword v131, v10, s[98:99] offset:512
	global_store_dword v229, v11, s[98:99] offset:512
	s_add_u32 s98, s98, 0x8000
	s_addc_u32 s99, s99, 0
	global_store_dword v128, v44, s[98:99]
	global_store_dword v130, v45, s[98:99]
	global_store_dword v131, v46, s[98:99]
	global_store_dword v229, v47, s[98:99]
	global_store_dword v128, v12, s[98:99] offset:512
	global_store_dword v130, v13, s[98:99] offset:512
	global_store_dword v131, v14, s[98:99] offset:512
	global_store_dword v229, v15, s[98:99] offset:512
	s_add_i32 s80, s80, s81
	s_add_i32 s82, s82, s34
	s_mov_b64 s[62:63], -1
	s_andn2_b64 vcc, exec, s[60:61]
	s_mov_b32 s85, s83
	s_cbranch_vccz .LBB0_2208

; __device__ __forceinline__ int crow(int r, int hi) { return (r & 3) + 8 * (r >> 2) + 4 * hi; }
; __device__ __forceinline__ void phase_gemm_res(const Params& p, int L, const bf16_t* __restrict__ A, int K, const bf16_t* __restrict__ WT, int gate_slot, bool from_input, bool xonly, LP lds) {
;     ...
;     const float* gate = mods + (size_t)mod_idx(row0) * 6144;
;     const float* resb = from_input ? in_row(p, row0) : s_row(p, row0);
;     float* sb = s_row(p, row0);
;     gemm8p(A + (size_t)row0 * K, K, WT + (size_t)col0 * K, K, K, lds, [&](int rr, int cc, int hi, f32x16 v) __attribute__((always_inline)) {
;       const int col = col0 + cc; const float g = gate[col];
; #pragma unroll
;       for (int r = 0; r < 16; ++r) { const size_t o = (size_t)(rr + crow(r, hi)) * DM + col; sb[o] = resb[o] + g * v[r]; }
.LBB0_2393:
	s_mul_hi_i32 s33, s62, 0x3e0f83e1
	s_lshr_b32 s63, s33, 31
	s_ashr_i32 s33, s33, 11
	s_add_i32 s68, s33, s63
	s_mul_i32 s33, s68, 0xffffdf00
	s_add_i32 s33, s33, s62
	s_cmpk_lt_i32 s33, 0x100
	s_cselect_b64 s[62:63], -1, 0
	s_and_b64 s[64:65], s[62:63], exec
	s_cselect_b32 s64, 4, s68
	s_mul_hi_i32 s65, s64, 0x6000
	s_mulk_i32 s64, 0x6000
	s_add_u32 s64, s77, s64
	s_addc_u32 s65, s78, s65
	s_ashr_i32 s69, s68, 31
	s_add_i32 s66, s33, 0xffffff00
	s_ashr_i32 s70, s33, 31
	s_and_b64 s[62:63], s[62:63], exec
	s_cselect_b32 s62, s33, s66
	s_cselect_b32 s33, 20, 25
	s_cselect_b32 s71, s80, s1
	s_cselect_b32 s86, s79, s0
	s_cselect_b32 s63, s70, 0
	s_lshl_b64 s[68:69], s[68:69], s33
	s_add_u32 s33, s86, s68
	s_addc_u32 s66, s71, s69
	s_lshl_b64 s[62:63], s[62:63], 12
	s_add_u32 s62, s33, s62
	s_addc_u32 s63, s66, s63
	s_nop 0
	v_lshl_add_u32 v128, v149, 2, v150
	v_add_u32_e32 v230, s67, v151
	v_lshlrev_b32_e32 v230, 2, v230
	v_lshl_add_u32 v128, v128, 12, v230
	v_add_u32_e32 v130, 0x1000, v128
	v_add_u32_e32 v131, 0x2000, v128
	v_add_u32_e32 v229, 0x3000, v128
	global_load_dword v231, v230, s[64:65]
	global_load_dword v232, v230, s[64:65] offset:512
	s_add_u32 s98, s62, 0x0
	s_addc_u32 s99, s63, 0
	global_load_dword v132, v128, s[98:99]
	global_load_dword v133, v130, s[98:99]
	global_load_dword v134, v131, s[98:99]
	global_load_dword v135, v229, s[98:99]
	global_load_dword v136, v128, s[98:99] offset:512
	global_load_dword v137, v130, s[98:99] offset:512
	global_load_dword v138, v131, s[98:99] offset:512
	global_load_dword v139, v229, s[98:99] offset:512
	s_add_u32 s98, s98, 0x8000
	s_addc_u32 s99, s99, 0
	global_load_dword v140, v128, s[98:99]
	global_load_dword v141, v130, s[98:99]
	global_load_dword v142, v131, s[98:99]
	global_load_dword v143, v229, s[98:99]
	global_load_dword v144, v128, s[98:99] offset:512
	global_load_dword v145, v130, s[98:99] offset:512
	global_load_dword v146, v131, s[98:99] offset:512
	global_load_dword v147, v229, s[98:99] offset:512
	s_add_u32 s98, s98, 0x8000
	s_addc_u32 s99, s99, 0
	global_load_dword v148, v128, s[98:99]
	global_load_dword v149, v130, s[98:99]
	global_load_dword v150, v131, s[98:99]
	global_load_dword v151, v229, s[98:99]
	global_load_dword v152, v128, s[98:99] offset:512
	global_load_dword v153, v130, s[98:99] offset:512
	global_load_dword v154, v131, s[98:99] offset:512
	global_load_dword v155, v229, s[98:99] offset:512
	s_add_u32 s98, s98, 0x8000
	s_addc_u32 s99, s99, 0
	global_load_dword v156, v128, s[98:99]
	global_load_dword v157, v130, s[98:99]
	global_load_dword v158, v131, s[98:99]
	global_load_dword v159, v229, s[98:99]
	global_load_dword v160, v128, s[98:99] offset:512
	global_load_dword v161, v130, s[98:99] offset:512
	global_load_dword v162, v131, s[98:99] offset:512
	global_load_dword v163, v229, s[98:99] offset:512
	s_add_u32 s98, s98, 0x8000
	s_addc_u32 s99, s99, 0
	global_load_dword v164, v128, s[98:99]
	global_load_dword v165, v130, s[98:99]
	global_load_dword v166, v131, s[98:99]
	global_load_dword v167, v229, s[98:99]
	global_load_dword v168, v128, s[98:99] offset:512
	global_load_dword v169, v130, s[98:99] offset:512
	global_load_dword v170, v131, s[98:99] offset:512
	global_load_dword v171, v229, s[98:99] offset:512
	s_add_u32 s98, s98, 0x8000
	s_addc_u32 s99, s99, 0
	global_load_dword v172, v128, s[98:99]
	global_load_dword v173, v130, s[98:99]
	global_load_dword v174, v131, s[98:99]
	global_load_dword v175, v229, s[98:99]
	global_load_dword v176, v128, s[98:99] offset:512
	global_load_dword v177, v130, s[98:99] offset:512
	global_load_dword v178, v131, s[98:99] offset:512
	global_load_dword v179, v229, s[98:99] offset:512
	s_add_u32 s98, s98, 0x8000
	s_addc_u32 s99, s99, 0
	global_load_dword v180, v128, s[98:99]
	global_load_dword v181, v130, s[98:99]
	global_load_dword v182, v131, s[98:99]
	global_load_dword v183, v229, s[98:99]
	global_load_dword v184, v128, s[98:99] offset:512
	global_load_dword v185, v130, s[98:99] offset:512
	global_load_dword v186, v131, s[98:99] offset:512
	global_load_dword v187, v229, s[98:99] offset:512
	s_add_u32 s98, s98, 0x8000
	s_addc_u32 s99, s99, 0
	global_load_dword v188, v128, s[98:99]
	global_load_dword v189, v130, s[98:99]
	global_load_dword v191, v131, s[98:99]
	global_load_dword v192, v229, s[98:99]
	global_load_dword v193, v128, s[98:99] offset:512
	global_load_dword v194, v130, s[98:99] offset:512
	global_load_dword v195, v131, s[98:99] offset:512
	global_load_dword v196, v229, s[98:99] offset:512
	s_add_u32 s98, s98, 0x48000
	s_addc_u32 s99, s99, 0
	global_load_dword v197, v128, s[98:99]
	global_load_dword v198, v130, s[98:99]
	global_load_dword v199, v131, s[98:99]
	global_load_dword v200, v229, s[98:99]
	global_load_dword v201, v128, s[98:99] offset:512
	global_load_dword v202, v130, s[98:99] offset:512
	global_load_dword v203, v131, s[98:99] offset:512
	global_load_dword v204, v229, s[98:99] offset:512
	s_add_u32 s98, s98, 0x8000
	s_addc_u32 s99, s99, 0
	global_load_dword v205, v128, s[98:99]
	global_load_dword v206, v130, s[98:99]
	global_load_dword v207, v131, s[98:99]
	global_load_dword v208, v229, s[98:99]
	global_load_dword v209, v128, s[98:99] offset:512
	global_load_dword v210, v130, s[98:99] offset:512
	global_load_dword v211, v131, s[98:99] offset:512
	global_load_dword v212, v229, s[98:99] offset:512
	s_add_u32 s98, s98, 0x8000
	s_addc_u32 s99, s99, 0
	global_load_dword v213, v128, s[98:99]
	global_load_dword v214, v130, s[98:99]
	global_load_dword v215, v131, s[98:99]
	global_load_dword v216, v229, s[98:99]
	global_load_dword v217, v128, s[98:99] offset:512
	global_load_dword v218, v130, s[98:99] offset:512
	global_load_dword v219, v131, s[98:99] offset:512
	global_load_dword v220, v229, s[98:99] offset:512
	s_add_u32 s98, s98, 0x8000
	s_addc_u32 s99, s99, 0
	global_load_dword v221, v128, s[98:99]
	global_load_dword v222, v130, s[98:99]
	global_load_dword v223, v131, s[98:99]
	global_load_dword v224, v229, s[98:99]
	global_load_dword v225, v128, s[98:99] offset:512
	global_load_dword v226, v130, s[98:99] offset:512
	global_load_dword v227, v131, s[98:99] offset:512
	global_load_dword v228, v229, s[98:99] offset:512
	s_waitcnt vmcnt(0)
; __device__ __forceinline__ int crow(int r, int hi) { return (r & 3) + 8 * (r >> 2) + 4 * hi; }
; __device__ __forceinline__ void phase_gemm_res(const Params& p, int L, const bf16_t* __restrict__ A, int K, const bf16_t* __restrict__ WT, int gate_slot, bool from_input, bool xonly, LP lds) {
;     ...
;       const int col = col0 + cc; const float g = gate[col];
; #pragma unroll
;       for (int r = 0; r < 16; ++r) { const size_t o = (size_t)(rr + crow(r, hi)) * DM + col; sb[o] = resb[o] + g * v[r]; }
	v_fma_f32 v112, v112, v231, v132
	v_fma_f32 v113, v113, v231, v133
	v_fma_f32 v114, v114, v231, v134
	v_fma_f32 v115, v115, v231, v135
	v_fma_f32 v80, v80, v232, v136
	v_fma_f32 v81, v81, v232, v137
	v_fma_f32 v82, v82, v232, v138
	v_fma_f32 v83, v83, v232, v139
	v_fma_f32 v116, v116, v231, v140
	v_fma_f32 v117, v117, v231, v141
	v_fma_f32 v118, v118, v231, v142
	v_fma_f32 v119, v119, v231, v143
	v_fma_f32 v84, v84, v232, v144
	v_fma_f32 v85, v85, v232, v145
	v_fma_f32 v86, v86, v232, v146
	v_fma_f32 v87, v87, v232, v147
	v_fma_f32 v120, v120, v231, v148
	v_fma_f32 v121, v121, v231, v149
	v_fma_f32 v122, v122, v231, v150
	v_fma_f32 v123, v123, v231, v151
	v_fma_f32 v88, v88, v232, v152
	v_fma_f32 v89, v89, v232, v153
	v_fma_f32 v90, v90, v232, v154
	v_fma_f32 v91, v91, v232, v155
	v_fma_f32 v124, v124, v231, v156
	v_fma_f32 v125, v125, v231, v157
	v_fma_f32 v126, v126, v231, v158
	v_fma_f32 v127, v127, v231, v159
	v_fma_f32 v92, v92, v232, v160
	v_fma_f32 v93, v93, v232, v161
	v_fma_f32 v94, v94, v232, v162
	v_fma_f32 v95, v95, v232, v163
	v_fma_f32 v96, v96, v231, v164
	v_fma_f32 v97, v97, v231, v165
	v_fma_f32 v98, v98, v231, v166
	v_fma_f32 v99, v99, v231, v167
	v_fma_f32 v64, v64, v232, v168
	v_fma_f32 v65, v65, v232, v169
	v_fma_f32 v66, v66, v232, v170
	v_fma_f32 v67, v67, v232, v171
	v_fma_f32 v100, v100, v231, v172
	v_fma_f32 v101, v101, v231, v173
	v_fma_f32 v102, v102, v231, v174
	v_fma_f32 v103, v103, v231, v175
	v_fma_f32 v68, v68, v232, v176
	v_fma_f32 v69, v69, v232, v177
	v_fma_f32 v70, v70, v232, v178
	v_fma_f32 v71, v71, v232, v179
	v_fma_f32 v104, v104, v231, v180
	v_fma_f32 v105, v105, v231, v181
	v_fma_f32 v106, v106, v231, v182
	v_fma_f32 v107, v107, v231, v183
	v_fma_f32 v72, v72, v232, v184
	v_fma_f32 v73, v73, v232, v185
	v_fma_f32 v74, v74, v232, v186
	v_fma_f32 v75, v75, v232, v187
	v_fma_f32 v108, v108, v231, v188
	v_fma_f32 v109, v109, v231, v189
	v_fma_f32 v110, v110, v231, v191
	v_fma_f32 v111, v111, v231, v192
	v_fma_f32 v76, v76, v232, v193
	v_fma_f32 v77, v77, v232, v194
	v_fma_f32 v78, v78, v232, v195
	v_fma_f32 v79, v79, v232, v196
	v_fma_f32 v48, v48, v231, v197
	v_fma_f32 v49, v49, v231, v198
	v_fma_f32 v50, v50, v231, v199
	v_fma_f32 v51, v51, v231, v200
	v_fma_f32 v16, v16, v232, v201
	v_fma_f32 v17, v17, v232, v202
	v_fma_f32 v18, v18, v232, v203
	v_fma_f32 v19, v19, v232, v204
	v_fma_f32 v52, v52, v231, v205
	v_fma_f32 v53, v53, v231, v206
	v_fma_f32 v54, v54, v231, v207
	v_fma_f32 v55, v55, v231, v208
	v_fma_f32 v20, v20, v232, v209
	v_fma_f32 v21, v21, v232, v210
	v_fma_f32 v22, v22, v232, v211
	v_fma_f32 v23, v23, v232, v212
	v_fma_f32 v56, v56, v231, v213
	v_fma_f32 v57, v57, v231, v214
	v_fma_f32 v58, v58, v231, v215
	v_fma_f32 v59, v59, v231, v216
	v_fma_f32 v24, v24, v232, v217
	v_fma_f32 v25, v25, v232, v218
	v_fma_f32 v26, v26, v232, v219
	v_fma_f32 v27, v27, v232, v220
	v_fma_f32 v60, v60, v231, v221
	v_fma_f32 v61, v61, v231, v222
	v_fma_f32 v62, v62, v231, v223
	v_fma_f32 v63, v63, v231, v224
	v_fma_f32 v28, v28, v232, v225
	v_fma_f32 v29, v29, v232, v226
	v_fma_f32 v30, v30, v232, v227
	v_fma_f32 v31, v31, v232, v228
	s_add_u32 s98, s62, 0xa0000
	s_addc_u32 s99, s63, 0
	global_load_dword v132, v128, s[98:99]
	global_load_dword v133, v130, s[98:99]
	global_load_dword v134, v131, s[98:99]
	global_load_dword v135, v229, s[98:99]
	global_load_dword v136, v128, s[98:99] offset:512
	global_load_dword v137, v130, s[98:99] offset:512
	global_load_dword v138, v131, s[98:99] offset:512
	global_load_dword v139, v229, s[98:99] offset:512
	s_add_u32 s98, s98, 0x8000
	s_addc_u32 s99, s99, 0
	global_load_dword v140, v128, s[98:99]
	global_load_dword v141, v130, s[98:99]
	global_load_dword v142, v131, s[98:99]
	global_load_dword v143, v229, s[98:99]
	global_load_dword v144, v128, s[98:99] offset:512
	global_load_dword v145, v130, s[98:99] offset:512
	global_load_dword v146, v131, s[98:99] offset:512
	global_load_dword v147, v229, s[98:99] offset:512
	s_add_u32 s98, s98, 0x8000
	s_addc_u32 s99, s99, 0
	global_load_dword v148, v128, s[98:99]
	global_load_dword v149, v130, s[98:99]
	global_load_dword v150, v131, s[98:99]
	global_load_dword v151, v229, s[98:99]
	global_load_dword v152, v128, s[98:99] offset:512
	global_load_dword v153, v130, s[98:99] offset:512
	global_load_dword v154, v131, s[98:99] offset:512
	global_load_dword v155, v229, s[98:99] offset:512
	s_add_u32 s98, s98, 0x8000
	s_addc_u32 s99, s99, 0
	global_load_dword v156, v128, s[98:99]
	global_load_dword v157, v130, s[98:99]
	global_load_dword v158, v131, s[98:99]
	global_load_dword v159, v229, s[98:99]
	global_load_dword v160, v128, s[98:99] offset:512
	global_load_dword v161, v130, s[98:99] offset:512
	global_load_dword v162, v131, s[98:99] offset:512
	global_load_dword v163, v229, s[98:99] offset:512
	s_waitcnt vmcnt(0)
; __device__ __forceinline__ int crow(int r, int hi) { return (r & 3) + 8 * (r >> 2) + 4 * hi; }
; __device__ __forceinline__ void phase_gemm_res(const Params& p, int L, const bf16_t* __restrict__ A, int K, const bf16_t* __restrict__ WT, int gate_slot, bool from_input, bool xonly, LP lds) {
;     ...
;       const int col = col0 + cc; const float g = gate[col];
; #pragma unroll
;       for (int r = 0; r < 16; ++r) { const size_t o = (size_t)(rr + crow(r, hi)) * DM + col; sb[o] = resb[o] + g * v[r]; }
	v_fma_f32 v32, v32, v231, v132
	v_fma_f32 v33, v33, v231, v133
	v_fma_f32 v34, v34, v231, v134
	v_fma_f32 v35, v35, v231, v135
	v_fma_f32 v0, v0, v232, v136
	v_fma_f32 v1, v1, v232, v137
	v_fma_f32 v2, v2, v232, v138
	v_fma_f32 v3, v3, v232, v139
	v_fma_f32 v36, v36, v231, v140
	v_fma_f32 v37, v37, v231, v141
	v_fma_f32 v38, v38, v231, v142
	v_fma_f32 v39, v39, v231, v143
	v_fma_f32 v4, v4, v232, v144
	v_fma_f32 v5, v5, v232, v145
	v_fma_f32 v6, v6, v232, v146
	v_fma_f32 v7, v7, v232, v147
	v_fma_f32 v40, v40, v231, v148
	v_fma_f32 v41, v41, v231, v149
	v_fma_f32 v42, v42, v231, v150
	v_fma_f32 v43, v43, v231, v151
	v_fma_f32 v8, v8, v232, v152
	v_fma_f32 v9, v9, v232, v153
	v_fma_f32 v10, v10, v232, v154
	v_fma_f32 v11, v11, v232, v155
	v_fma_f32 v44, v44, v231, v156
	v_fma_f32 v45, v45, v231, v157
	v_fma_f32 v46, v46, v231, v158
	v_fma_f32 v47, v47, v231, v159
	v_fma_f32 v12, v12, v232, v160
	v_fma_f32 v13, v13, v232, v161
	v_fma_f32 v14, v14, v232, v162
	v_fma_f32 v15, v15, v232, v163
	s_add_u32 s98, s62, 0x0
	s_addc_u32 s99, s63, 0
	global_store_dword v128, v112, s[98:99]
	global_store_dword v130, v113, s[98:99]
	global_store_dword v131, v114, s[98:99]
	global_store_dword v229, v115, s[98:99]
	global_store_dword v128, v80, s[98:99] offset:512
	global_store_dword v130, v81, s[98:99] offset:512
	global_store_dword v131, v82, s[98:99] offset:512
	global_store_dword v229, v83, s[98:99] offset:512
	s_add_u32 s98, s98, 0x8000
	s_addc_u32 s99, s99, 0
	global_store_dword v128, v116, s[98:99]
	global_store_dword v130, v117, s[98:99]
	global_store_dword v131, v118, s[98:99]
	global_store_dword v229, v119, s[98:99]
	global_store_dword v128, v84, s[98:99] offset:512
	global_store_dword v130, v85, s[98:99] offset:512
	global_store_dword v131, v86, s[98:99] offset:512
	global_store_dword v229, v87, s[98:99] offset:512
	s_add_u32 s98, s98, 0x8000
	s_addc_u32 s99, s99, 0
	global_store_dword v128, v120, s[98:99]
	global_store_dword v130, v121, s[98:99]
	global_store_dword v131, v122, s[98:99]
	global_store_dword v229, v123, s[98:99]
	global_store_dword v128, v88, s[98:99] offset:512
	global_store_dword v130, v89, s[98:99] offset:512
	global_store_dword v131, v90, s[98:99] offset:512
	global_store_dword v229, v91, s[98:99] offset:512
	s_add_u32 s98, s98, 0x8000
	s_addc_u32 s99, s99, 0
	global_store_dword v128, v124, s[98:99]
	global_store_dword v130, v125, s[98:99]
	global_store_dword v131, v126, s[98:99]
	global_store_dword v229, v127, s[98:99]
	global_store_dword v128, v92, s[98:99] offset:512
	global_store_dword v130, v93, s[98:99] offset:512
	global_store_dword v131, v94, s[98:99] offset:512
	global_store_dword v229, v95, s[98:99] offset:512
	s_add_u32 s98, s98, 0x8000
	s_addc_u32 s99, s99, 0
	global_store_dword v128, v96, s[98:99]
	global_store_dword v130, v97, s[98:99]
	global_store_dword v131, v98, s[98:99]
	global_store_dword v229, v99, s[98:99]
	global_store_dword v128, v64, s[98:99] offset:512
	global_store_dword v130, v65, s[98:99] offset:512
	global_store_dword v131, v66, s[98:99] offset:512
	global_store_dword v229, v67, s[98:99] offset:512
	s_add_u32 s98, s98, 0x8000
	s_addc_u32 s99, s99, 0
	global_store_dword v128, v100, s[98:99]
	global_store_dword v130, v101, s[98:99]
	global_store_dword v131, v102, s[98:99]
	global_store_dword v229, v103, s[98:99]
	global_store_dword v128, v68, s[98:99] offset:512
	global_store_dword v130, v69, s[98:99] offset:512
	global_store_dword v131, v70, s[98:99] offset:512
	global_store_dword v229, v71, s[98:99] offset:512
	s_add_u32 s98, s98, 0x8000
	s_addc_u32 s99, s99, 0
	global_store_dword v128, v104, s[98:99]
	global_store_dword v130, v105, s[98:99]
	global_store_dword v131, v106, s[98:99]
	global_store_dword v229, v107, s[98:99]
	global_store_dword v128, v72, s[98:99] offset:512
	global_store_dword v130, v73, s[98:99] offset:512
	global_store_dword v131, v74, s[98:99] offset:512
	global_store_dword v229, v75, s[98:99] offset:512
; __device__ __forceinline__ int crow(int r, int hi) { return (r & 3) + 8 * (r >> 2) + 4 * hi; }
; __device__ __forceinline__ void phase_gemm_res(const Params& p, int L, const bf16_t* __restrict__ A, int K, const bf16_t* __restrict__ WT, int gate_slot, bool from_input, bool xonly, LP lds) {
;     ...
;   for (int t = blockIdx.x; t < 512; t += gridDim.x) {
;     ...
;       const int col = col0 + cc; const float g = gate[col];
; #pragma unroll
;       for (int r = 0; r < 16; ++r) { const size_t o = (size_t)(rr + crow(r, hi)) * DM + col; sb[o] = resb[o] + g * v[r]; }
;     }, pre, hasn ? A + (size_t)rown * K : nullptr, hasn ? WT + (size_t)coln * K : nullptr);
	s_add_u32 s98, s98, 0x8000
	s_addc_u32 s99, s99, 0
	global_store_dword v128, v108, s[98:99]
	global_store_dword v130, v109, s[98:99]
	global_store_dword v131, v110, s[98:99]
	global_store_dword v229, v111, s[98:99]
	global_store_dword v128, v76, s[98:99] offset:512
	global_store_dword v130, v77, s[98:99] offset:512
	global_store_dword v131, v78, s[98:99] offset:512
	global_store_dword v229, v79, s[98:99] offset:512
	s_add_u32 s98, s98, 0x48000
	s_addc_u32 s99, s99, 0
	global_store_dword v128, v48, s[98:99]
	global_store_dword v130, v49, s[98:99]
	global_store_dword v131, v50, s[98:99]
	global_store_dword v229, v51, s[98:99]
	global_store_dword v128, v16, s[98:99] offset:512
	global_store_dword v130, v17, s[98:99] offset:512
	global_store_dword v131, v18, s[98:99] offset:512
	global_store_dword v229, v19, s[98:99] offset:512
	s_add_u32 s98, s98, 0x8000
	s_addc_u32 s99, s99, 0
	global_store_dword v128, v52, s[98:99]
	global_store_dword v130, v53, s[98:99]
	global_store_dword v131, v54, s[98:99]
	global_store_dword v229, v55, s[98:99]
	global_store_dword v128, v20, s[98:99] offset:512
	global_store_dword v130, v21, s[98:99] offset:512
	global_store_dword v131, v22, s[98:99] offset:512
	global_store_dword v229, v23, s[98:99] offset:512
	s_add_u32 s98, s98, 0x8000
	s_addc_u32 s99, s99, 0
	global_store_dword v128, v56, s[98:99]
	global_store_dword v130, v57, s[98:99]
	global_store_dword v131, v58, s[98:99]
	global_store_dword v229, v59, s[98:99]
	global_store_dword v128, v24, s[98:99] offset:512
	global_store_dword v130, v25, s[98:99] offset:512
	global_store_dword v131, v26, s[98:99] offset:512
	global_store_dword v229, v27, s[98:99] offset:512
	s_add_u32 s98, s98, 0x8000
	s_addc_u32 s99, s99, 0
	global_store_dword v128, v60, s[98:99]
	global_store_dword v130, v61, s[98:99]
	global_store_dword v131, v62, s[98:99]
	global_store_dword v229, v63, s[98:99]
	global_store_dword v128, v28, s[98:99] offset:512
	global_store_dword v130, v29, s[98:99] offset:512
	global_store_dword v131, v30, s[98:99] offset:512
	global_store_dword v229, v31, s[98:99] offset:512
	s_add_u32 s98, s98, 0x8000
	s_addc_u32 s99, s99, 0
	global_store_dword v128, v32, s[98:99]
	global_store_dword v130, v33, s[98:99]
	global_store_dword v131, v34, s[98:99]
	global_store_dword v229, v35, s[98:99]
	global_store_dword v128, v0, s[98:99] offset:512
	global_store_dword v130, v1, s[98:99] offset:512
	global_store_dword v131, v2, s[98:99] offset:512
	global_store_dword v229, v3, s[98:99] offset:512
	s_add_u32 s98, s98, 0x8000
	s_addc_u32 s99, s99, 0
	global_store_dword v128, v36, s[98:99]
	global_store_dword v130, v37, s[98:99]
	global_store_dword v131, v38, s[98:99]
	global_store_dword v229, v39, s[98:99]
	global_store_dword v128, v4, s[98:99] offset:512
	global_store_dword v130, v5, s[98:99] offset:512
	global_store_dword v131, v6, s[98:99] offset:512
	global_store_dword v229, v7, s[98:99] offset:512
	s_add_u32 s98, s98, 0x8000
	s_addc_u32 s99, s99, 0
	global_store_dword v128, v40, s[98:99]
	global_store_dword v130, v41, s[98:99]
	global_store_dword v131, v42, s[98:99]
	global_store_dword v229, v43, s[98:99]
	global_store_dword v128, v8, s[98:99] offset:512
	global_store_dword v130, v9, s[98:99] offset:512
	global_store_dword v131, v10, s[98:99] offset:512
	global_store_dword v229, v11, s[98:99] offset:512
	s_add_u32 s98, s98, 0x8000
	s_addc_u32 s99, s99, 0
	global_store_dword v128, v44, s[98:99]
	global_store_dword v130, v45, s[98:99]
	global_store_dword v131, v46, s[98:99]
	global_store_dword v229, v47, s[98:99]
	global_store_dword v128, v12, s[98:99] offset:512
	global_store_dword v130, v13, s[98:99] offset:512
	global_store_dword v131, v14, s[98:99] offset:512
	global_store_dword v229, v15, s[98:99] offset:512
	s_add_i32 s81, s81, s82
	s_add_i32 s84, s84, s34
	s_mov_b64 s[62:63], -1
	s_andn2_b64 vcc, exec, s[60:61]
	s_mov_b32 s33, s85
	s_cbranch_vccz .LBB0_2406
